# v32 + P0 x-cast loop: the row's 8 f32 loads issued up front with counted vmcnt waits (each was followed by vmcnt(0)); cvt/address temporaries moved to free registers
# speedup vs baseline: 1.0002x; 1.0002x over previous
.LBB0_50:
	global_load_dwordx4 v[14:17], v[4:5], off offset:-4096
	global_load_dwordx4 v[18:21], v[4:5], off offset:-3072
	global_load_dwordx4 v[22:25], v[4:5], off offset:-2048
	global_load_dwordx4 v[26:29], v[4:5], off offset:-1024
	global_load_dwordx4 v[30:33], v[4:5], off
	global_load_dwordx4 v[34:37], v[4:5], off offset:1024
	global_load_dwordx4 v[38:41], v[4:5], off offset:2048
	global_load_dwordx4 v[42:45], v[4:5], off offset:3072
	v_lshl_add_u64 v[52:53], s[88:89], 0, v[6:7]
	v_add_co_u32_e32 v46, vcc, s7, v52
	s_nop 1
	v_addc_co_u32_e32 v47, vcc, 0, v53, vcc
	s_waitcnt vmcnt(7)
	v_cvt_pk_bf16_f32 v48, v14, v15
	v_cvt_pk_bf16_f32 v49, v16, v17
	global_store_dwordx2 v[46:47], v[48:49], off
	v_mul_f32_e32 v2, v15, v15
	s_waitcnt lgkmcnt(0)
	v_mul_f32_e32 v13, v17, v17
	v_fmac_f32_e32 v2, v14, v14
	v_fmac_f32_e32 v13, v16, v16
	v_add_f32_e32 v2, v2, v13
	s_waitcnt vmcnt(6)
	v_cvt_pk_bf16_f32 v50, v18, v19
	v_cvt_pk_bf16_f32 v51, v20, v21
	global_store_dwordx2 v[46:47], v[50:51], off offset:512
	v_mul_f32_e32 v13, v19, v19
	v_mul_f32_e32 v14, v21, v21
	v_fmac_f32_e32 v13, v18, v18
	v_fmac_f32_e32 v14, v20, v20
	v_add_f32_e32 v13, v13, v14
	v_add_f32_e32 v2, v2, v13
	s_waitcnt vmcnt(5)
	v_cvt_pk_bf16_f32 v48, v22, v23
	v_cvt_pk_bf16_f32 v49, v24, v25
	global_store_dwordx2 v[46:47], v[48:49], off offset:1024
	v_mul_f32_e32 v13, v23, v23
	v_mul_f32_e32 v14, v25, v25
	v_fmac_f32_e32 v13, v22, v22
	v_fmac_f32_e32 v14, v24, v24
	v_add_f32_e32 v13, v13, v14
	v_add_f32_e32 v2, v2, v13
	s_waitcnt vmcnt(4)
	v_cvt_pk_bf16_f32 v50, v26, v27
	v_cvt_pk_bf16_f32 v51, v28, v29
	global_store_dwordx2 v[46:47], v[50:51], off offset:1536
	v_mul_f32_e32 v13, v27, v27
	v_mul_f32_e32 v14, v29, v29
	v_fmac_f32_e32 v13, v26, v26
	v_fmac_f32_e32 v14, v28, v28
	v_add_f32_e32 v13, v13, v14
	v_add_f32_e32 v2, v2, v13
	s_waitcnt vmcnt(3)
	v_cvt_pk_bf16_f32 v48, v30, v31
	v_cvt_pk_bf16_f32 v49, v32, v33
	global_store_dwordx2 v[46:47], v[48:49], off offset:2048
	v_mul_f32_e32 v13, v31, v31
	v_mul_f32_e32 v14, v33, v33
	v_fmac_f32_e32 v13, v30, v30
	v_fmac_f32_e32 v14, v32, v32
	v_add_f32_e32 v13, v13, v14
	v_add_f32_e32 v2, v2, v13
	s_waitcnt vmcnt(2)
	v_cvt_pk_bf16_f32 v50, v34, v35
	v_cvt_pk_bf16_f32 v51, v36, v37
	global_store_dwordx2 v[46:47], v[50:51], off offset:2560
	v_mul_f32_e32 v13, v35, v35
	v_mul_f32_e32 v14, v37, v37
	v_fmac_f32_e32 v13, v34, v34
	v_fmac_f32_e32 v14, v36, v36
	v_add_f32_e32 v13, v13, v14
	v_add_f32_e32 v2, v2, v13
	s_waitcnt vmcnt(1)
	v_cvt_pk_bf16_f32 v48, v38, v39
	v_cvt_pk_bf16_f32 v49, v40, v41
	global_store_dwordx2 v[46:47], v[48:49], off offset:3072
	v_mul_f32_e32 v13, v39, v39
	v_mul_f32_e32 v14, v41, v41
	v_fmac_f32_e32 v13, v38, v38
	v_fmac_f32_e32 v14, v40, v40
	v_add_f32_e32 v13, v13, v14
	v_add_f32_e32 v2, v2, v13
	s_waitcnt vmcnt(0)
	v_mul_f32_e32 v13, v43, v43
	v_mul_f32_e32 v14, v45, v45
	v_fmac_f32_e32 v13, v42, v42
	v_fmac_f32_e32 v14, v44, v44
	v_add_f32_e32 v13, v13, v14
	v_add_f32_e32 v2, v2, v13
	ds_bpermute_b32 v13, v1, v2
	v_cvt_pk_bf16_f32 v14, v42, v43
	v_cvt_pk_bf16_f32 v15, v44, v45
	global_store_dwordx2 v[46:47], v[14:15], off offset:3584
	s_waitcnt lgkmcnt(0)
	v_add_f32_e32 v2, v2, v13
	ds_bpermute_b32 v13, v8, v2
	s_waitcnt lgkmcnt(0)
	v_add_f32_e32 v2, v2, v13
	ds_bpermute_b32 v13, v9, v2
	s_waitcnt lgkmcnt(0)
	v_add_f32_e32 v2, v2, v13
	ds_bpermute_b32 v13, v10, v2
	s_waitcnt lgkmcnt(0)
	v_add_f32_e32 v2, v2, v13
	ds_bpermute_b32 v13, v11, v2
	s_waitcnt lgkmcnt(0)
	v_add_f32_e32 v2, v2, v13
	ds_bpermute_b32 v13, v12, v2
	s_and_saveexec_b64 s[18:19], s[0:1]
	s_cbranch_execz .LBB0_49
	s_waitcnt lgkmcnt(0)
	v_add_f32_e32 v2, v2, v13
	v_mul_f32_e32 v2, 0x4b800000, v2
	v_rndne_f32_e32 v2, v2
	v_mul_f32_e32 v13, 0x2f800000, v2
	v_floor_f32_e32 v13, v13
	v_fmac_f32_e32 v2, 0xcf800000, v13
	v_cvt_u32_f32_e32 v14, v2
	v_cvt_u32_f32_e32 v15, v13
	s_add_u32 s20, s88, s2
	s_addc_u32 s21, s89, s3
	global_store_dwordx2 v3, v[14:15], s[20:21]
	s_branch .LBB0_49
